# dilated branch: K/V chunk loads software-prefetched one chunk ahead, bias LDS reads hoisted, bpermute replaced by permlane32_swap; MLA loop pipelined
# speedup vs baseline: 1.0588x; 1.0177x over previous
; #define LAS __attribute__((address_space(3)))
; __device__ __forceinline__ void dil_unit(int hs, int un, bf16_t* BIG, bf16_t* ZA, const float* __restrict__ BT, LAS char* lds) {
;     ...
;         const int item = wid + 8 * k, g = item >> 4, b = item & 15, sh = 2 * g, L = SEQ >> sh;
;         const int p = b >> (4 - sh), sub = b & ((16 >> sh) - 1), m0 = (T0 >> sh) + 32 * sub;
;         const size_t rowbase = (size_t)p * L;
;         bf16_t* Qg = BIG + (size_t)(0 * 3 + g) * GSZ; const bf16_t* Kg = BIG + (size_t)(1 * 3 + g) * GSZ; const bf16_t* Vg = BIG + (size_t)(2 * 3 + g) * GSZ;
;         const size_t qrow = rowbase + m0 + r32;
;         bf16x8 qf[4];
; #pragma unroll
;         for (int s = 0; s < 4; ++s) qf[s] = *(const bf16x8*)(Qg + qrow * 512 + hs * 64 + 16 * s + 8 * hi);
;         float mrun = NEGB, l = 0.f; f32x16 o0 = {}, o1 = {};
;         const LAS float* tg = tab + g * 192;
.LBB0_534:
	s_lshl_b32 s14, s38, 3
	s_add_i32 s15, s14, s37
	s_ashr_i32 s14, s15, 4
	s_lshl_b32 s39, s14, 1
	s_and_b32 s15, s15, 15
	s_sub_i32 s17, 4, s39
	s_lshr_b32 s40, s15, s17
	s_lshr_b32 s17, 16, s39
	s_add_i32 s17, s17, -1
	s_and_b32 s15, s17, s15
	s_lshr_b32 s16, 0x4000, s39
	s_lshr_b32 s41, s27, s39
	s_lshl_b32 s42, s15, 5
	s_ashr_i32 s15, s14, 31
	s_add_i32 s46, s42, s41
	s_mul_i32 s47, s40, s16
	s_lshl_b64 s[16:17], s[14:15], 24
	s_add_u32 s44, s19, s16
	v_add_u32_e32 v95, s46, v85
	s_addc_u32 s45, s20, s17
	v_add_lshl_u32 v0, v95, s47, 10
	v_lshl_add_u64 v[2:3], s[44:45], 0, v[0:1]
	v_lshl_add_u64 v[96:97], s[12:13], 1, v[2:3]
	v_mov_b32_e32 v93, v1
	v_lshl_add_u64 v[2:3], v[96:97], 0, v[92:93]
	global_load_dwordx4 v[64:67], v[2:3], off
	global_load_dwordx4 v[68:71], v[2:3], off offset:32
	global_load_dwordx4 v[72:75], v[2:3], off offset:64
	global_load_dwordx4 v[76:79], v[2:3], off offset:96
	v_lshl_add_u64 v[2:3], v[90:91], 0, s[16:17]
	s_mov_b64 s[44:45], 0x3000000
	v_lshl_add_u64 v[98:99], v[2:3], 0, s[44:45]
	v_lshl_add_u64 v[2:3], v[86:87], 0, s[16:17]
	s_mov_b64 s[16:17], 0x6000000
	v_lshl_add_u64 v[100:101], v[2:3], 0, s[16:17]
	s_add_i32 s16, s42, s47
	v_mov_b32_e32 v14, v1
	v_mov_b32_e32 v15, v1
	s_mul_i32 s56, s14, 0x300
	s_add_i32 s15, s46, 0xffffff80
	s_add_i32 s16, s16, s41
	s_add_i32 s46, s46, s47
	v_mov_b32_e32 v0, v1
	v_mov_b32_e32 v2, v1
	v_mov_b32_e32 v3, v1
	v_mov_b32_e32 v4, v1
	v_mov_b32_e32 v5, v1
	v_mov_b32_e32 v6, v1
	v_mov_b32_e32 v7, v1
	v_mov_b32_e32 v8, v1
	v_mov_b32_e32 v9, v1
	v_mov_b32_e32 v10, v1
	v_mov_b32_e32 v11, v1
	v_mov_b32_e32 v12, v1
	v_mov_b32_e32 v13, v1
	v_mov_b64_e32 v[30:31], v[14:15]
	v_mov_b64_e32 v[46:47], v[14:15]
	v_add_u32_e32 v93, s56, v89
	v_add_u32_e32 v106, s16, v102
	v_add_u32_e32 v107, s46, v103
	v_mov_b32_e32 v108, 0
	v_mov_b32_e32 v109, 0xf149f2ca
	s_mov_b32 s16, 0
	v_mov_b64_e32 v[28:29], v[12:13]
	v_mov_b64_e32 v[26:27], v[10:11]
	v_mov_b64_e32 v[24:25], v[8:9]
	v_mov_b64_e32 v[22:23], v[6:7]
	v_mov_b64_e32 v[20:21], v[4:5]
	v_mov_b64_e32 v[18:19], v[2:3]
	v_mov_b64_e32 v[16:17], v[0:1]
	v_mov_b64_e32 v[44:45], v[12:13]
	v_mov_b64_e32 v[42:43], v[10:11]
	v_mov_b64_e32 v[40:41], v[8:9]
	v_mov_b64_e32 v[38:39], v[6:7]
	v_mov_b64_e32 v[36:37], v[4:5]
	v_mov_b64_e32 v[34:35], v[2:3]
	v_mov_b64_e32 v[32:33], v[0:1]
	s_mov_b32 s98, 0
	s_branch .LBB0_536

; __device__ __forceinline__ void dil_unit(int hs, int un, bf16_t* BIG, bf16_t* ZA, const float* __restrict__ BT, LAS char* lds) {
;     ...
;             const int ks0 = m0 - 128 + 32 * c; if (ks0 < 0) continue;
;             const bf16_t* kp = Kg + (rowbase + ks0 + r32) * 512 + hs * 64 + 8 * hi;
;             bf16x8 ka[4];
; #pragma unroll
;             for (int s = 0; s < 4; ++s) ka[s] = *(const bf16x8*)(kp + 16 * s);
;             u32x4 vv[4];
; #pragma unroll
;             for (int i = 0; i < 4; ++i) vv[i] = *(const u32x4*)(Vg + (rowbase + ks0 + (lane >> 3) + 8 * i) * 512 + hs * 64 + (lane & 7) * 8);
.LBB0_536:
	s_add_i32 s17, s15, s16
	s_cmp_lt_i32 s17, 0
	s_cbranch_scc1 .LBB0_535
	s_cmp_lg_u32 s98, 0
	s_cbranch_scc1 .Ldil_ready
	v_add_u32_e32 v154, s16, v107
	v_mov_b32_e32 v155, v1
	v_lshlrev_b64 v[156:157], 10, v[154:155]
	v_lshl_add_u64 v[156:157], v[98:99], 0, v[156:157]
	global_load_dwordx4 v[122:125], v[156:157], off
	global_load_dwordx4 v[126:129], v[156:157], off offset:32
	global_load_dwordx4 v[130:133], v[156:157], off offset:64
	global_load_dwordx4 v[134:137], v[156:157], off offset:96
	v_add_u32_e32 v154, s16, v106
	v_lshlrev_b64 v[158:159], 10, v[154:155]
	v_lshl_add_u64 v[158:159], v[100:101], 0, v[158:159]
	s_mov_b64 s[44:45], 0x2000
	v_lshl_add_u64 v[160:161], v[158:159], 0, s[44:45]
	s_mov_b64 s[44:45], 0x4000
	v_lshl_add_u64 v[162:163], v[158:159], 0, s[44:45]
	s_mov_b64 s[44:45], 0x6000
	v_lshl_add_u64 v[164:165], v[158:159], 0, s[44:45]
	global_load_dwordx4 v[138:141], v[158:159], off
	global_load_dwordx4 v[142:145], v[160:161], off
	global_load_dwordx4 v[146:149], v[162:163], off
	global_load_dwordx4 v[150:153], v[164:165], off
.Ldil_ready:
	s_waitcnt vmcnt(0)
	v_mov_b64_e32 v[48:49], v[122:123]
	v_mov_b64_e32 v[50:51], v[124:125]
	v_mov_b64_e32 v[110:111], v[126:127]
	v_mov_b64_e32 v[112:113], v[128:129]
	v_mov_b64_e32 v[114:115], v[130:131]
	v_mov_b64_e32 v[116:117], v[132:133]
	v_mov_b64_e32 v[118:119], v[134:135]
	v_mov_b64_e32 v[120:121], v[136:137]
	v_mov_b64_e32 v[2:3], v[138:139]
	v_mov_b64_e32 v[4:5], v[140:141]
	v_mov_b64_e32 v[6:7], v[142:143]
	v_mov_b64_e32 v[8:9], v[144:145]
	v_mov_b64_e32 v[10:11], v[146:147]
	v_mov_b64_e32 v[12:13], v[148:149]
	v_mov_b64_e32 v[80:81], v[150:151]
	v_mov_b64_e32 v[82:83], v[152:153]
	s_mov_b32 s98, 0
	s_cmpk_eq_i32 s16, 0x80
	s_cbranch_scc1 .Ldil_nopf
	s_add_i32 s17, s16, 32
	v_add_u32_e32 v154, s17, v107
	v_mov_b32_e32 v155, v1
	v_lshlrev_b64 v[156:157], 10, v[154:155]
	v_lshl_add_u64 v[156:157], v[98:99], 0, v[156:157]
	global_load_dwordx4 v[122:125], v[156:157], off
	global_load_dwordx4 v[126:129], v[156:157], off offset:32
	global_load_dwordx4 v[130:133], v[156:157], off offset:64
	global_load_dwordx4 v[134:137], v[156:157], off offset:96
	v_add_u32_e32 v154, s17, v106
	v_lshlrev_b64 v[158:159], 10, v[154:155]
	v_lshl_add_u64 v[158:159], v[100:101], 0, v[158:159]
	s_mov_b64 s[44:45], 0x2000
	v_lshl_add_u64 v[160:161], v[158:159], 0, s[44:45]
	s_mov_b64 s[44:45], 0x4000
	v_lshl_add_u64 v[162:163], v[158:159], 0, s[44:45]
	s_mov_b64 s[44:45], 0x6000
	v_lshl_add_u64 v[164:165], v[158:159], 0, s[44:45]
	global_load_dwordx4 v[138:141], v[158:159], off
	global_load_dwordx4 v[142:145], v[160:161], off
	global_load_dwordx4 v[146:149], v[162:163], off
	global_load_dwordx4 v[150:153], v[164:165], off
	s_mov_b32 s98, 1
; #define LAS __attribute__((address_space(3)))
; __device__ __forceinline__ float fast_exp2(float x) { return __builtin_amdgcn_exp2f(x); }
; __device__ __forceinline__ int crow(int r, int hi) { return (r & 3) + 8 * (r >> 2) + 4 * hi; }
; __device__ __forceinline__ s16x4 vtr(const LAS char* p) { typedef short v4i16_t __attribute__((ext_vector_type(4))); return __builtin_bit_cast(s16x4, __builtin_amdgcn_ds_read_tr16_b64_v4i16((LAS v4i16_t*)p)); }
; __device__ __forceinline__ bf16x8 cat8(s16x4 a, s16x4 b) { return (bf16x8){a[0], a[1], a[2], a[3], b[0], b[1], b[2], b[3]}; }
; __device__ __forceinline__ bf16x8 packp(const f32x16& p, int b) { u32x4 w; w.x = cvt_pk_bf16(p[b], p[b + 1]); w.y = cvt_pk_bf16(p[b + 2], p[b + 3]); w.z = cvt_pk_bf16(p[b + 4], p[b + 5]); w.w = cvt_pk_bf16(p[b + 6], p[b + 7]); return __builtin_bit_cast(bf16x8, w); }
; __device__ __forceinline__ void dil_unit(int hs, int un, bf16_t* BIG, bf16_t* ZA, const float* __restrict__ BT, LAS char* lds) {
;     ...
;             f32x16 sc = {};
; #pragma unroll
;             for (int s = 0; s < 4; ++s) sc = __builtin_amdgcn_mfma_f32_32x32x16_bf16(ka[s], qf[s], sc, 0, 0, 0);
; #pragma unroll
;             for (int r = 0; r < 16; ++r) sc[r] += tg[160 - 32 * c + r32 - crow(r, hi)];
;             float rm = max16(sc); rm = fmaxf(rm, __shfl_xor(rm, 32));
;             const float mn = fmaxf(mrun, rm), alpha = fast_exp2(mrun - mn); mrun = mn;
;             float ps = 0.f;
; #pragma unroll
;             for (int r = 0; r < 16; ++r) { sc[r] = fast_exp2(sc[r] - mn); ps += sc[r]; }
;             l = l * alpha + ps; o0 *= alpha; o1 *= alpha;
;             const bf16x8 pb0 = packp(sc, 0), pb1 = packp(sc, 8);
; #pragma unroll
;             for (int i = 0; i < 4; ++i) *(LAS u32x4*)(vst + ((lane >> 3) + 8 * i) * VP + (lane & 7) * 16) = vv[i];
;             asm volatile("s_waitcnt lgkmcnt(0)" ::: "memory");
; #pragma unroll
;             for (int ks = 0; ks < 2; ++ks) { const bf16x8 pb = ks == 0 ? pb0 : pb1;
;                 const LAS char* vp = vst + va_off + ks * 16 * VP;
;                 const bf16x8 a0 = cat8(vtr(vp), vtr(vp + 8 * VP)), a1 = cat8(vtr(vp + 64), vtr(vp + 8 * VP + 64));
;                 o0 = __builtin_amdgcn_mfma_f32_32x32x16_bf16(a0, pb, o0, 0, 0, 0); o1 = __builtin_amdgcn_mfma_f32_32x32x16_bf16(a1, pb, o1, 0, 0, 0); }
;             asm volatile("s_waitcnt lgkmcnt(0)" ::: "memory");
.Ldil_nopf:
	ds_read2_b32 v[166:167], v93 offset0:26 offset1:27
	ds_read2_b32 v[168:169], v93 offset0:24 offset1:25
	ds_read2_b32 v[170:171], v93 offset0:18 offset1:19
	ds_read2_b32 v[172:173], v93 offset0:16 offset1:17
	ds_read2_b32 v[174:175], v93 offset0:10 offset1:11
	ds_read2_b32 v[188:189], v93 offset0:8 offset1:9
	ds_read2_b32 v[190:191], v93 offset0:2 offset1:3
	ds_read2_b32 v[192:193], v93 offset1:1
	v_mfma_f32_32x32x16_bf16 v[48:63], v[48:51], v[64:67], 0
	v_mfma_f32_32x32x16_bf16 v[48:63], v[110:113], v[68:71], v[48:63]
	v_mfma_f32_32x32x16_bf16 v[48:63], v[114:117], v[72:75], v[48:63]
	v_mfma_f32_32x32x16_bf16 v[48:63], v[118:121], v[76:79], v[48:63]
	s_waitcnt lgkmcnt(0)
	s_nop 10
	v_add_f32_e32 v0, v48, v167
	v_add_f32_e32 v48, v49, v166
	v_add_f32_e32 v49, v50, v169
	v_add_f32_e32 v50, v51, v168
	v_add_f32_e32 v51, v52, v171
	v_add_f32_e32 v52, v53, v170
	v_add_f32_e32 v53, v54, v173
	v_add_f32_e32 v54, v55, v172
	v_add_f32_e32 v55, v56, v175
	v_add_f32_e32 v56, v57, v174
	v_add_f32_e32 v57, v58, v189
	v_add_f32_e32 v58, v59, v188
	v_max_f32_e32 v110, v57, v58
	v_add_f32_e32 v59, v60, v191
	v_add_f32_e32 v60, v61, v190
	v_add_f32_e32 v15, v62, v193
	v_add_f32_e32 v61, v63, v192
	v_max_f32_e32 v111, v15, v61
	v_max_f32_e32 v14, v49, v50
	v_max_f32_e32 v62, v53, v54
	v_max_f32_e32 v63, v55, v56
	v_max3_f32 v111, v59, v60, v111
	v_max3_f32 v14, v0, v48, v14
	v_max3_f32 v62, v51, v52, v62
	v_max3_f32 v63, v63, v110, v111
	v_max3_f32 v14, v14, v62, v63
	v_mov_b32_e32 v62, v14
	s_nop 1
	v_permlane32_swap_b32_e32 v14, v62
	v_max3_f32 v14, v109, v14, v62
	v_sub_f32_e32 v0, v0, v14
	v_exp_f32_e32 v63, v0
	v_sub_f32_e32 v0, v48, v14
	v_sub_f32_e32 v62, v109, v14
	v_exp_f32_e32 v109, v0
	v_sub_f32_e32 v0, v49, v14
	v_exp_f32_e32 v110, v0
	v_sub_f32_e32 v0, v50, v14
	v_exp_f32_e32 v111, v0
	v_sub_f32_e32 v0, v51, v14
	v_exp_f32_e32 v112, v0
	v_sub_f32_e32 v0, v52, v14
	v_exp_f32_e32 v113, v0
	v_sub_f32_e32 v0, v53, v14
	v_exp_f32_e32 v114, v0
	v_sub_f32_e32 v0, v54, v14
	v_exp_f32_e32 v115, v0
	v_sub_f32_e32 v0, v55, v14
	v_exp_f32_e32 v116, v0
	v_sub_f32_e32 v0, v56, v14
	v_exp_f32_e32 v56, v0
	v_sub_f32_e32 v0, v57, v14
	v_exp_f32_e32 v57, v0
	v_sub_f32_e32 v0, v58, v14
	v_exp_f32_e32 v58, v0
	v_sub_f32_e32 v0, v59, v14
	v_exp_f32_e32 v59, v0
	v_sub_f32_e32 v0, v60, v14
	v_exp_f32_e32 v60, v0
	v_sub_f32_e32 v0, v15, v14
	v_exp_f32_e32 v15, v0
	v_sub_f32_e32 v0, v61, v14
	v_exp_f32_e32 v61, v0
	v_cvt_pk_bf16_f32 v52, v63, v109
	v_cvt_pk_bf16_f32 v53, v110, v111
	v_cvt_pk_bf16_f32 v54, v112, v113
	v_cvt_pk_bf16_f32 v55, v114, v115
	v_cvt_pk_bf16_f32 v48, v116, v56
	v_cvt_pk_bf16_f32 v49, v57, v58
	v_cvt_pk_bf16_f32 v50, v59, v60
	v_cvt_pk_bf16_f32 v51, v15, v61
	ds_write_b128 v104, v[2:5]
	ds_write_b128 v104, v[6:9] offset:1536
	ds_write_b128 v104, v[10:13] offset:3072
	ds_write_b128 v104, v[80:83] offset:4608
	v_add_f32_e32 v2, 0, v63
	v_add_f32_e32 v2, v109, v2
	v_add_f32_e32 v2, v110, v2
	v_add_f32_e32 v2, v111, v2
	v_add_f32_e32 v2, v112, v2
	v_add_f32_e32 v2, v113, v2
	v_add_f32_e32 v2, v114, v2
	v_add_f32_e32 v2, v115, v2
	v_add_f32_e32 v2, v116, v2
	v_add_f32_e32 v2, v56, v2
	v_add_f32_e32 v2, v57, v2
	v_add_f32_e32 v2, v58, v2
	v_add_f32_e32 v2, v59, v2
	v_add_f32_e32 v2, v60, v2
	v_add_f32_e32 v2, v15, v2
	s_waitcnt lgkmcnt(0)
	v_exp_f32_e32 v0, v62
	v_add_f32_e32 v10, v61, v2
	ds_read_b64_tr_b16 v[2:3], v105
	ds_read_b64_tr_b16 v[4:5], v105 offset:1536
	ds_read_b64_tr_b16 v[6:7], v105 offset:64
	ds_read_b64_tr_b16 v[8:9], v105 offset:1600
	v_mov_b32_e32 v109, v14
	v_pk_mul_f32 v[46:47], v[46:47], v[0:1] op_sel_hi:[1,0]
	v_pk_mul_f32 v[44:45], v[44:45], v[0:1] op_sel_hi:[1,0]
	v_pk_mul_f32 v[42:43], v[42:43], v[0:1] op_sel_hi:[1,0]
	v_pk_mul_f32 v[40:41], v[40:41], v[0:1] op_sel_hi:[1,0]
	v_pk_mul_f32 v[38:39], v[38:39], v[0:1] op_sel_hi:[1,0]
	v_pk_mul_f32 v[36:37], v[36:37], v[0:1] op_sel_hi:[1,0]
	v_pk_mul_f32 v[34:35], v[34:35], v[0:1] op_sel_hi:[1,0]
	v_pk_mul_f32 v[32:33], v[32:33], v[0:1] op_sel_hi:[1,0]
	v_pk_mul_f32 v[30:31], v[30:31], v[0:1] op_sel_hi:[1,0]
	v_pk_mul_f32 v[28:29], v[28:29], v[0:1] op_sel_hi:[1,0]
	v_pk_mul_f32 v[26:27], v[26:27], v[0:1] op_sel_hi:[1,0]
	v_pk_mul_f32 v[24:25], v[24:25], v[0:1] op_sel_hi:[1,0]
	v_pk_mul_f32 v[22:23], v[22:23], v[0:1] op_sel_hi:[1,0]
	v_pk_mul_f32 v[20:21], v[20:21], v[0:1] op_sel_hi:[1,0]
	v_pk_mul_f32 v[18:19], v[18:19], v[0:1] op_sel_hi:[1,0]
	v_pk_mul_f32 v[16:17], v[16:17], v[0:1] op_sel_hi:[1,0]
	s_waitcnt lgkmcnt(2)
	v_mfma_f32_32x32x16_bf16 v[32:47], v[2:5], v[52:55], v[32:47]
	v_fmac_f32_e32 v10, v108, v0
	v_mov_b32_e32 v108, v10
	s_waitcnt lgkmcnt(0)
	v_mfma_f32_32x32x16_bf16 v[16:31], v[6:9], v[52:55], v[16:31]
	ds_read_b64_tr_b16 v[2:3], v105 offset:3072
	ds_read_b64_tr_b16 v[4:5], v105 offset:4608
	ds_read_b64_tr_b16 v[6:7], v105 offset:3136
	ds_read_b64_tr_b16 v[8:9], v105 offset:4672
	s_waitcnt lgkmcnt(0)
	s_waitcnt lgkmcnt(2)
	v_mfma_f32_32x32x16_bf16 v[32:47], v[2:5], v[48:51], v[32:47]
	s_waitcnt lgkmcnt(0)
	v_mfma_f32_32x32x16_bf16 v[16:31], v[6:9], v[48:51], v[16:31]
	s_branch .LBB0_535

; __global__ void __launch_bounds__(NWAVES * 64, 2) fwd_mega(Args a_unused) {
	.amdhsa_kernel _Z8fwd_mega4Args
		.amdhsa_group_segment_fixed_size 0
		.amdhsa_private_segment_fixed_size 0
		.amdhsa_kernarg_size 408
		.amdhsa_user_sgpr_count 2
		.amdhsa_user_sgpr_dispatch_ptr 0
		.amdhsa_user_sgpr_queue_ptr 0
		.amdhsa_user_sgpr_kernarg_segment_ptr 1
		.amdhsa_user_sgpr_dispatch_id 0
		.amdhsa_user_sgpr_kernarg_preload_length 0
		.amdhsa_user_sgpr_kernarg_preload_offset 0
		.amdhsa_user_sgpr_private_segment_size 0
		.amdhsa_uses_dynamic_stack 0
		.amdhsa_enable_private_segment 0
		.amdhsa_system_sgpr_workgroup_id_x 1
		.amdhsa_system_sgpr_workgroup_id_y 0
		.amdhsa_system_sgpr_workgroup_id_z 0
		.amdhsa_system_sgpr_workgroup_info 0
		.amdhsa_system_vgpr_workitem_id 2
		.amdhsa_next_free_vgpr 256
		.amdhsa_next_free_sgpr 100
		.amdhsa_accum_offset 256
		.amdhsa_reserve_vcc 1
		.amdhsa_float_round_mode_32 0
		.amdhsa_float_round_mode_16_64 0
		.amdhsa_float_denorm_mode_32 3
		.amdhsa_float_denorm_mode_16_64 3
		.amdhsa_dx10_clamp 1
		.amdhsa_ieee_mode 1
		.amdhsa_fp16_overflow 0
		.amdhsa_tg_split 0
		.amdhsa_exception_fp_ieee_invalid_op 0
		.amdhsa_exception_fp_denorm_src 0
		.amdhsa_exception_fp_ieee_div_zero 0
		.amdhsa_exception_fp_ieee_overflow 0
		.amdhsa_exception_fp_ieee_underflow 0
		.amdhsa_exception_fp_ieee_inexact 0
		.amdhsa_exception_int_div_zero 0
	.end_amdhsa_kernel

; __global__ void __launch_bounds__(NWAVES * 64, 2) fwd_mega(Args a_unused) {
amdhsa.kernels:
  - .agpr_count:     0
    .args:
      - .offset:         0
        .size:           152
        .value_kind:     by_value
      - .offset:         152
        .size:           4
        .value_kind:     hidden_block_count_x
      - .offset:         156
        .size:           4
        .value_kind:     hidden_block_count_y
      - .offset:         160
        .size:           4
        .value_kind:     hidden_block_count_z
      - .offset:         164
        .size:           2
        .value_kind:     hidden_group_size_x
      - .offset:         166
        .size:           2
        .value_kind:     hidden_group_size_y
      - .offset:         168
        .size:           2
        .value_kind:     hidden_group_size_z
      - .offset:         170
        .size:           2
        .value_kind:     hidden_remainder_x
      - .offset:         172
        .size:           2
        .value_kind:     hidden_remainder_y
      - .offset:         174
        .size:           2
        .value_kind:     hidden_remainder_z
      - .offset:         192
        .size:           8
        .value_kind:     hidden_global_offset_x
      - .offset:         200
        .size:           8
        .value_kind:     hidden_global_offset_y
      - .offset:         208
        .size:           8
        .value_kind:     hidden_global_offset_z
      - .offset:         216
        .size:           2
        .value_kind:     hidden_grid_dims
      - .offset:         240
        .size:           8
        .value_kind:     hidden_multigrid_sync_arg
      - .offset:         272
        .size:           4
        .value_kind:     hidden_dynamic_lds_size
    .group_segment_fixed_size: 0
    .kernarg_segment_align: 8
    .kernarg_segment_size: 408
    .language:       OpenCL C
    .language_version:
      - 2
      - 0
    .max_flat_workgroup_size: 512
    .name:           _Z8fwd_mega4Args
    .private_segment_fixed_size: 0
    .sgpr_count:     106
    .sgpr_spill_count: 22
    .symbol:         _Z8fwd_mega4Args.kd
    .uniform_work_group_size: 1
    .uses_dynamic_stack: false
    .vgpr_count:     256
    .vgpr_spill_count: 0
    .wavefront_size: 64
